# hand-written grid barriers: pollers sleep 4 (256 clocks) between polls instead of 1, less traffic on the generation word while the release lands
# baseline (speedup 1.0000x reference)
.Lgb0_spin:
	global_load_dword v2, v[184:185], off sc1
	s_add_i32 s0, s0, 1
	s_waitcnt vmcnt(0)
	v_cmp_ne_u32_e32 vcc, s10, v2
	s_cbranch_vccnz .Lgb0_acq
	s_sleep 4
	s_cmp_lt_u32 s0, 0x8000
	s_cbranch_scc1 .Lgb0_spin
